# v35 plus tile-blocked lane-linear layout of the GATES scratch (written by the input-projection epilogue, read only by the branch-GEMM epilogue): 4x256B pieces per wave access, 2 KiB contiguous per row
# speedup vs baseline: 1.0055x; 1.0055x over previous
.LBB9_100:
	v_mov_b32_e32 v42, v191
	v_mov_b32_e32 v148, v190
	s_lshl_b32 s6, s4, 8
	s_or_b32 s6, s6, s35
	v_lshlrev_b32_e32 v149, 3, v42
	v_add_u32_e32 v146, s6, v149
	v_ashrrev_i32_e32 v147, 31, v146
	v_add_u32_e32 v184, s38, v148
	v_lshl_add_u64 v[46:47], v[146:147], 2, s[16:17]
	v_ashrrev_i32_e32 v185, 31, v184
	global_load_dwordx4 v[50:53], v[46:47], off offset:16
	global_load_dwordx4 v[58:61], v[46:47], off
	global_load_dwordx4 v[42:45], v[46:47], off offset:528
	s_nop 0
	global_load_dwordx4 v[46:49], v[46:47], off offset:512
	v_lshrrev_b32_e32 v208, 8, v184
	v_lshrrev_b32_e32 v209, 8, v146
	v_lshl_add_u32 v208, v208, 4, v209
	v_bfe_u32 v209, v184, 6, 1
	v_bfe_u32 v207, v146, 5, 2
	v_lshl_add_u32 v209, v209, 2, v207
	v_lshrrev_b32_e32 v207, 1, v209
	v_lshl_add_u32 v208, v208, 2, v207
	v_and_b32_e32 v209, 1, v209
	v_lshl_add_u32 v208, v208, 2, v209
	v_lshlrev_b32_e32 v208, 13, v208
	v_bfe_u32 v209, v146, 3, 2
	v_lshl_add_u32 v208, v209, 9, v208
	v_and_b32_e32 v209, 15, v184
	v_lshl_add_u32 v208, v209, 4, v208
	v_lshlrev_b32_e32 v209, 7, v184
	v_sub_u32_e32 v208, v208, v209
	v_ashrrev_i32_e32 v209, 31, v208
	v_lshl_add_u64 v[180:181], s[86:87], 0, v[208:209]
	v_lshlrev_b64 v[146:147], 7, v[184:185]
	v_lshl_add_u64 v[146:147], v[180:181], 0, v[146:147]
	global_load_dwordx4 v[162:165], v[146:147], off
	s_ashr_i32 s4, s4, 2
	v_add_u32_e32 v182, s39, v149
	v_ashrrev_i32_e32 v183, 31, v182
	v_lshrrev_b32_e32 v211, 8, v184
	v_lshrrev_b32_e32 v210, 8, v182
	v_lshl_add_u32 v211, v211, 2, v210
	v_bfe_u32 v210, v184, 6, 1
	v_lshl_add_u32 v211, v211, 1, v210
	v_bfe_u32 v210, v182, 5, 2
	v_lshl_add_u32 v211, v211, 2, v210
	v_lshlrev_b32_e32 v211, 15, v211
	v_lshl_add_u32 v211, v244, 4, v211
	s_cmp_lt_i32 s4, 1
	v_lshlrev_b64 v[148:149], 10, v[184:185]
	s_cselect_b64 s[8:9], -1, 0
	v_lshl_add_u64 v[188:189], v[148:149], 0, v[182:183]
	v_mov_b32_e32 v186, v211
	s_and_b64 vcc, exec, s[8:9]
	s_cbranch_vccnz .LBB9_102
	global_load_dwordx4 v[158:161], v186, s[18:19] offset:1024
	global_load_dwordx4 v[166:169], v186, s[18:19]
	s_branch .LBB9_103

.LBB9_116:
	s_nop 1
	v_add_u32_e32 v132, 16, v184
	v_ashrrev_i32_e32 v133, 31, v132
	v_lshlrev_b64 v[130:131], 7, v[132:133]
	v_lshl_add_u64 v[130:131], v[180:181], 0, v[130:131]
	global_load_dwordx4 v[146:149], v[130:131], off
	s_and_b64 vcc, exec, s[6:7]
	s_mov_b64 s[28:29], -1
	s_cbranch_vccnz .LBB9_118
	s_mov_b64 s[28:29], 0

.LBB9_132:
	s_nop 1
	v_add_u32_e32 v116, 32, v184
	v_ashrrev_i32_e32 v117, 31, v116
	v_lshlrev_b64 v[114:115], 7, v[116:117]
	v_lshl_add_u64 v[114:115], v[180:181], 0, v[114:115]
	global_load_dwordx4 v[130:133], v[114:115], off
	s_and_b64 vcc, exec, s[6:7]
	s_mov_b64 s[28:29], -1
	s_cbranch_vccnz .LBB9_134
	s_mov_b64 s[28:29], 0

.LBB9_140:
	s_nop 1
	v_add_u32_e32 v150, 48, v184
	v_ashrrev_i32_e32 v151, 31, v150
	v_lshlrev_b64 v[148:149], 7, v[150:151]
	v_lshl_add_u64 v[148:149], v[180:181], 0, v[148:149]
	global_load_dwordx4 v[164:167], v[148:149], off
	s_and_b64 vcc, exec, s[6:7]
	s_mov_b64 s[28:29], -1
	s_cbranch_vccnz .LBB9_150
	s_mov_b64 s[28:29], 0

.LBB9_164:
	s_nop 1
	v_add_u32_e32 v84, 0x80, v184
	v_ashrrev_i32_e32 v85, 31, v84
	v_lshlrev_b64 v[82:83], 7, v[84:85]
	v_lshl_add_u64 v[82:83], v[180:181], 0, v[82:83]
	global_load_dwordx4 v[98:101], v[82:83], off
	s_and_b64 vcc, exec, s[6:7]
	s_mov_b64 s[28:29], -1
	s_cbranch_vccnz .LBB9_166
	s_mov_b64 s[28:29], 0

.LBB9_172:
	s_nop 1
	v_add_u32_e32 v118, 0x90, v184
	v_ashrrev_i32_e32 v119, 31, v118
	v_lshlrev_b64 v[116:117], 7, v[118:119]
	v_lshl_add_u64 v[116:117], v[180:181], 0, v[116:117]
	global_load_dwordx4 v[132:135], v[116:117], off
	s_and_b64 vcc, exec, s[6:7]
	s_mov_b64 s[28:29], -1
	s_cbranch_vccnz .LBB9_182
	s_mov_b64 s[28:29], 0

.LBB9_196:
	s_nop 1
	v_add_u32_e32 v36, 0xa0, v184
	v_ashrrev_i32_e32 v37, 31, v36
	v_lshlrev_b64 v[34:35], 7, v[36:37]
	v_lshl_add_u64 v[34:35], v[180:181], 0, v[34:35]
	global_load_dwordx4 v[66:69], v[34:35], off
	s_and_b64 vcc, exec, s[6:7]
	s_mov_b64 s[28:29], -1
	s_cbranch_vccnz .LBB9_198
	s_mov_b64 s[28:29], 0

.LBB9_204:
	s_nop 1
	v_add_u32_e32 v86, 0xb0, v184
	v_ashrrev_i32_e32 v87, 31, v86
	v_lshlrev_b64 v[84:85], 7, v[86:87]
	v_lshl_add_u64 v[84:85], v[180:181], 0, v[84:85]
	global_load_dwordx4 v[100:103], v[84:85], off
	s_and_b64 vcc, exec, s[6:7]
	s_mov_b64 s[28:29], -1
	s_cbranch_vccnz .LBB9_214
	s_mov_b64 s[28:29], 0

.LBB9_646:
	v_bfe_u32 v141, v126, 16, 1
	v_add3_u32 v126, v126, v141, s1
	v_bfe_u32 v141, v127, 16, 1
	v_add3_u32 v127, v127, v141, s1
	v_bfe_u32 v141, v128, 16, 1
	v_add3_u32 v141, v128, v141, s1
	v_bfe_u32 v128, v129, 16, 1
	s_lshl_b32 s8, s8, 8
	v_add3_u32 v128, v129, v128, s1
	v_bfe_u32 v129, v122, 16, 1
	s_add_i32 s8, s8, s36
	v_add3_u32 v151, v122, v129, s1
	v_bfe_u32 v122, v123, 16, 1
	v_add_u32_e32 v140, s8, v140
	s_add_i32 s8, s11, s37
	v_add3_u32 v122, v123, v122, s1
	v_bfe_u32 v123, v124, 16, 1
	v_lshl_add_u32 v142, v150, 3, s8
	v_add3_u32 v152, v124, v123, s1
	v_bfe_u32 v123, v125, 16, 1
	v_ashrrev_i32_e32 v143, 31, v142
	v_add3_u32 v123, v125, v123, s1
	s_cmp_gt_i32 s10, 8
	s_cbranch_scc0 .Lgl_proj
	v_lshrrev_b32_e32 v200, 8, v140
	v_lshrrev_b32_e32 v201, 8, v142
	v_lshl_add_u32 v200, v200, 4, v201
	v_bfe_u32 v201, v140, 6, 1
	v_bfe_u32 v202, v142, 5, 2
	v_lshl_add_u32 v201, v201, 2, v202
	v_lshrrev_b32_e32 v202, 1, v201
	v_lshl_add_u32 v200, v200, 2, v202
	v_and_b32_e32 v201, 1, v201
	v_lshl_add_u32 v200, v200, 2, v201
	v_lshlrev_b32_e32 v200, 13, v200
	v_bfe_u32 v201, v142, 3, 2
	v_lshl_add_u32 v200, v201, 9, v200
	v_and_b32_e32 v201, 15, v140
	v_lshl_add_u32 v200, v201, 4, v200
	v_mov_b32_e32 v201, 0
	v_lshl_add_u64 v[142:143], s[26:27], 0, v[200:201]
	v_mov_b32_e32 v140, 0
	s_movk_i32 s28, 0x40
	s_branch .Lgl_done
.Lgl_proj:
	v_lshl_add_u64 v[142:143], v[142:143], 1, s[26:27]
.Lgl_done:
	s_cmp_eq_u32 s10, 8
	v_mad_i64_i32 v[144:145], s[8:9], s28, v140, 0
	v_and_b32_e32 v127, 0xffff0000, v127
	v_and_b32_e32 v128, 0xffff0000, v128
	v_and_b32_e32 v122, 0xffff0000, v122
	v_and_b32_e32 v124, 0xffff0000, v123
	s_cselect_b64 s[30:31], -1, 0
	s_cmp_lg_u32 s10, 8
	v_lshl_add_u64 v[144:145], v[144:145], 1, v[142:143]
	v_or_b32_sdwa v154, v127, v126 dst_sel:DWORD dst_unused:UNUSED_PAD src0_sel:DWORD src1_sel:WORD_1
	v_or_b32_sdwa v155, v128, v141 dst_sel:DWORD dst_unused:UNUSED_PAD src0_sel:DWORD src1_sel:WORD_1
	v_or_b32_sdwa v156, v122, v151 dst_sel:DWORD dst_unused:UNUSED_PAD src0_sel:DWORD src1_sel:WORD_1
	v_or_b32_sdwa v157, v124, v152 dst_sel:DWORD dst_unused:UNUSED_PAD src0_sel:DWORD src1_sel:WORD_1
	v_mov_b32_e32 v123, 0
	global_store_dwordx4 v[144:145], v[154:157], off
	s_cbranch_scc1 .LBB9_648
	v_and_b32_e32 v126, 0xffff0000, v126
	v_pk_mul_f32 v[126:127], v[126:127], v[126:127]
	v_and_b32_e32 v129, 0xffff0000, v141
	v_pk_mul_f32 v[128:129], v[128:129], v[128:129]
	v_add_f32_e32 v126, v126, v127
	v_and_b32_e32 v123, 0xffff0000, v151
	v_add_f32_e32 v126, v129, v126
	v_pk_mul_f32 v[122:123], v[122:123], v[122:123]
	v_add_f32_e32 v126, v128, v126
	v_and_b32_e32 v125, 0xffff0000, v152
	v_add_f32_e32 v123, v123, v126
	v_pk_mul_f32 v[124:125], v[124:125], v[124:125]
	v_add_f32_e32 v122, v122, v123
	v_add_f32_e32 v122, v125, v122
	v_add_f32_e32 v123, v124, v122
